# MLA attention: the 12 K-fragment LDS reads of a tile are issued right after the step barrier, ahead of the next-tile global loads
# baseline (speedup 1.0000x reference)
.LBB0_1438:
	s_mov_b64 s[22:23], 0x6000
	s_add_i32 s92, s92, 2
	s_addk_i32 s93, 0x80
	v_lshl_add_u64 v[130:131], v[130:131], 0, s[22:23]
	v_lshl_add_u64 v[132:133], v[132:133], 0, s[62:63]
	s_cmp_lt_u32 s94, s89
	v_lshl_add_u64 v[134:135], v[134:135], 0, s[62:63]
	s_cbranch_scc0 .LBB0_1420
.LBB0_1439:
	s_add_i32 s22, s93, 0xffffff81
	s_cmp_gt_i32 s22, s91
	s_cbranch_scc1 .Lmla_skiprd_e
	v_add_u32_e32 v96, v141, v126
	ds_read_b128 v[192:195], v96 offset:0
	ds_read_b128 v[196:199], v96 offset:32
	ds_read_b128 v[200:203], v96 offset:64
	ds_read_b128 v[204:207], v96 offset:96
	ds_read_b128 v[208:211], v96 offset:128
	ds_read_b128 v[212:215], v96 offset:160
	ds_read_b128 v[216:219], v96 offset:6656
	ds_read_b128 v[162:165], v96 offset:6688
	ds_read_b128 v[166:169], v96 offset:6720
	ds_read_b128 v[170:173], v96 offset:6752
	ds_read_b128 v[174:177], v96 offset:6784
	ds_read_b128 v[178:181], v96 offset:6816
.Lmla_skiprd_e:
	s_add_i32 s94, s92, -1
	s_cmp_lt_u32 s94, s89
	s_cselect_b64 s[70:71], -1, 0
	s_cmp_ge_u32 s94, s89
	s_cbranch_scc1 .LBB0_1445
	v_add_co_u32_e32 v32, vcc, 0xffffb000, v130
	s_nop 1
	v_addc_co_u32_e32 v33, vcc, -1, v131, vcc
	global_load_dwordx4 v[108:111], v[32:33], off
	s_and_saveexec_b64 s[72:73], s[8:9]
	s_cbranch_execz .LBB0_1442
	v_add_co_u32_e32 v32, vcc, 0xffffd000, v130
	s_nop 1
	v_addc_co_u32_e32 v33, vcc, -1, v131, vcc
	global_load_dwordx4 v[116:119], v[32:33], off

.LBB0_1445:
	s_add_i32 s22, s93, 0xffffff81
	s_cmp_gt_i32 s22, s91
	s_cbranch_scc1 .LBB0_1451
	v_xor_b32_e32 v32, 0x80000000, v148
	v_mov_b32_e32 v33, v32
	v_mov_b32_e32 v34, v32
	v_mov_b32_e32 v35, v32
	v_mov_b32_e32 v36, v32
	v_mov_b32_e32 v37, v32
	v_mov_b32_e32 v38, v32
	v_mov_b32_e32 v39, v32
	v_mov_b32_e32 v40, v32
	v_mov_b32_e32 v41, v32
	v_mov_b32_e32 v42, v32
	v_mov_b32_e32 v43, v32
	v_mov_b32_e32 v44, v32
	v_mov_b32_e32 v45, v32
	v_mov_b32_e32 v46, v32
	v_mov_b32_e32 v47, v32
	v_add_u32_e32 v182, v143, v144
	v_add_u32_e32 v183, 0x3000, v182
	v_add_u32_e32 v184, 0x4000, v182
	v_xor_b32_e32 v185, 32, v225
	v_lshlrev_b32_e32 v185, 2, v185
	s_sub_i32 s22, s93, 64
	s_cmp_le_i32 s22, s90
	s_waitcnt lgkmcnt(11)
	v_mfma_f32_32x32x16_bf16 v[48:63], v[192:195], v[80:83], v[32:47]
	ds_read2_b64 v[192:195], v183 offset0:128 offset1:130
	s_waitcnt lgkmcnt(11)
	v_mfma_f32_32x32x16_bf16 v[48:63], v[196:199], v[84:87], v[48:63]
	ds_read2_b64 v[196:199], v184 offset0:160 offset1:162
	s_waitcnt lgkmcnt(11)
	v_mfma_f32_32x32x16_bf16 v[48:63], v[200:203], v[88:91], v[48:63]
	ds_read2_b64 v[200:203], v183 offset0:132 offset1:134
	s_waitcnt lgkmcnt(11)
	v_mfma_f32_32x32x16_bf16 v[48:63], v[204:207], v[92:95], v[48:63]
	ds_read2_b64 v[204:207], v184 offset0:164 offset1:166
	s_waitcnt lgkmcnt(11)
	v_mfma_f32_32x32x16_bf16 v[48:63], v[208:211], v[100:103], v[48:63]
	ds_read2_b64 v[208:211], v183 offset0:136 offset1:138
	s_waitcnt lgkmcnt(11)
	v_mfma_f32_32x32x16_bf16 v[48:63], v[212:215], v[104:107], v[48:63]
	ds_read2_b64 v[212:215], v184 offset0:168 offset1:170
	s_waitcnt lgkmcnt(11)
	v_mfma_f32_32x32x16_bf16 v[32:47], v[216:219], v[80:83], v[32:47]
	ds_read2_b64 v[216:219], v183 offset0:140 offset1:142
	s_waitcnt lgkmcnt(11)
	v_mfma_f32_32x32x16_bf16 v[32:47], v[162:165], v[84:87], v[32:47]
	ds_read2_b64 v[162:165], v184 offset0:172 offset1:174
	s_waitcnt lgkmcnt(11)
	v_mfma_f32_32x32x16_bf16 v[32:47], v[166:169], v[88:91], v[32:47]
	s_waitcnt lgkmcnt(10)
	v_mfma_f32_32x32x16_bf16 v[32:47], v[170:173], v[92:95], v[32:47]
	s_waitcnt lgkmcnt(9)
	v_mfma_f32_32x32x16_bf16 v[32:47], v[174:177], v[100:103], v[32:47]
	s_waitcnt lgkmcnt(8)
	v_mfma_f32_32x32x16_bf16 v[32:47], v[178:181], v[104:107], v[32:47]
	s_cbranch_scc1 .LBB0_1448
	v_add_u32_e32 v96, s93, v140
	v_add_u32_e32 v99, 0xffffffa1, v96
	v_add_u32_e32 v98, 0xffffff81, v96
	v_cmp_le_i32_e32 vcc, v99, v142
	s_nop 6
	v_cndmask_b32_e32 v32, v235, v32, vcc
	v_cmp_lt_i32_e32 vcc, v98, v142
	s_nop 1
	v_cndmask_b32_e32 v49, v235, v49, vcc
	v_cmp_le_i32_e32 vcc, v98, v142
	v_add_u32_e32 v98, 0xffffffa2, v96
	s_nop 0
	v_cndmask_b32_e32 v48, v235, v48, vcc
	v_cmp_le_i32_e32 vcc, v98, v142
	v_add_u32_e32 v98, 0xffffff83, v96
	s_nop 0
	v_cndmask_b32_e32 v33, v235, v33, vcc
	v_cmp_le_i32_e32 vcc, v98, v142
	v_add_u32_e32 v98, 0xffffffa3, v96
	s_nop 0
	v_cndmask_b32_e32 v50, v235, v50, vcc
	v_cmp_le_i32_e32 vcc, v98, v142
	v_add_u32_e32 v98, 0xffffff84, v96
	s_nop 0
	v_cndmask_b32_e32 v34, v235, v34, vcc
	v_cmp_le_i32_e32 vcc, v98, v142
	v_add_u32_e32 v98, 0xffffffa4, v96
	s_nop 0
	v_cndmask_b32_e32 v51, v235, v51, vcc
	v_cmp_le_i32_e32 vcc, v98, v142
	v_add_u32_e32 v98, 0xffffff89, v96
	s_nop 0
	v_cndmask_b32_e32 v35, v235, v35, vcc
	v_cmp_le_i32_e32 vcc, v98, v142
	v_add_u32_e32 v98, 0xffffffa9, v96
	s_nop 0
	v_cndmask_b32_e32 v52, v235, v52, vcc
	v_cmp_le_i32_e32 vcc, v98, v142
	v_add_u32_e32 v98, 0xffffff8a, v96
	s_nop 0
	v_cndmask_b32_e32 v36, v235, v36, vcc
	v_cmp_le_i32_e32 vcc, v98, v142
	v_add_u32_e32 v98, 0xffffffaa, v96
	s_nop 0
	v_cndmask_b32_e32 v53, v235, v53, vcc
	v_cmp_le_i32_e32 vcc, v98, v142
	v_add_u32_e32 v98, 0xffffff8b, v96
	s_nop 0
	v_cndmask_b32_e32 v37, v235, v37, vcc
	v_cmp_le_i32_e32 vcc, v98, v142
	v_add_u32_e32 v98, 0xffffffab, v96
	s_nop 0
	v_cndmask_b32_e32 v54, v235, v54, vcc
	v_cmp_le_i32_e32 vcc, v98, v142
	v_add_u32_e32 v98, 0xffffff8c, v96
	s_nop 0
	v_cndmask_b32_e32 v38, v235, v38, vcc
	v_cmp_le_i32_e32 vcc, v98, v142
	v_add_u32_e32 v98, 0xffffffac, v96
	s_nop 0
	v_cndmask_b32_e32 v55, v235, v55, vcc
	v_cmp_le_i32_e32 vcc, v98, v142
	v_add_u32_e32 v98, 0xffffff91, v96
	s_nop 0
	v_cndmask_b32_e32 v39, v235, v39, vcc
	v_cmp_le_i32_e32 vcc, v98, v142
	v_add_u32_e32 v98, 0xffffffb1, v96
	s_nop 0
	v_cndmask_b32_e32 v56, v235, v56, vcc
	v_cmp_le_i32_e32 vcc, v98, v142
	v_add_u32_e32 v98, 0xffffff92, v96
	s_nop 0
	v_cndmask_b32_e32 v40, v235, v40, vcc
	v_cmp_le_i32_e32 vcc, v98, v142
	v_add_u32_e32 v98, 0xffffffb2, v96
	s_nop 0
	v_cndmask_b32_e32 v57, v235, v57, vcc
	v_cmp_le_i32_e32 vcc, v98, v142
	v_add_u32_e32 v98, 0xffffff93, v96
	s_nop 0
	v_cndmask_b32_e32 v41, v235, v41, vcc
	v_cmp_le_i32_e32 vcc, v98, v142
	v_add_u32_e32 v98, 0xffffffb3, v96
	s_nop 0
	v_cndmask_b32_e32 v58, v235, v58, vcc
	v_cmp_le_i32_e32 vcc, v98, v142
	v_add_u32_e32 v98, 0xffffff94, v96
	s_nop 0
	v_cndmask_b32_e32 v42, v235, v42, vcc
	v_cmp_le_i32_e32 vcc, v98, v142
	v_add_u32_e32 v98, 0xffffffb4, v96
	s_nop 0
	v_cndmask_b32_e32 v59, v235, v59, vcc
	v_cmp_le_i32_e32 vcc, v98, v142
	v_add_u32_e32 v98, 0xffffff99, v96
	s_nop 0
	v_cndmask_b32_e32 v43, v235, v43, vcc
	v_cmp_le_i32_e32 vcc, v98, v142
	v_add_u32_e32 v98, 0xffffffb9, v96
	s_nop 0
	v_cndmask_b32_e32 v60, v235, v60, vcc
	v_cmp_le_i32_e32 vcc, v98, v142
	v_add_u32_e32 v98, 0xffffff9a, v96
	s_nop 0
	v_cndmask_b32_e32 v44, v235, v44, vcc
	v_cmp_le_i32_e32 vcc, v98, v142
	v_add_u32_e32 v98, 0xffffffba, v96
	s_nop 0
	v_cndmask_b32_e32 v61, v235, v61, vcc
	v_cmp_le_i32_e32 vcc, v98, v142
	v_add_u32_e32 v98, 0xffffff9b, v96
	s_nop 0
	v_cndmask_b32_e32 v45, v235, v45, vcc
	v_cmp_le_i32_e32 vcc, v98, v142
	v_add_u32_e32 v98, 0xffffffbb, v96
	s_nop 0
	v_cndmask_b32_e32 v62, v235, v62, vcc
	v_cmp_le_i32_e32 vcc, v98, v142
	v_add_u32_e32 v98, 0xffffff9c, v96
	v_add_u32_e32 v96, 0xffffffbc, v96
	v_cndmask_b32_e32 v46, v235, v46, vcc
	v_cmp_le_i32_e32 vcc, v98, v142
	s_nop 1
	v_cndmask_b32_e32 v63, v235, v63, vcc
	v_cmp_le_i32_e32 vcc, v96, v142
	s_nop 1
	v_cndmask_b32_e32 v47, v235, v47, vcc

.LBB0_1457:
	s_andn2_b64 vcc, exec, s[72:73]
	s_waitcnt lgkmcnt(0)
	s_barrier
	s_cbranch_vccnz .LBB0_1438
	s_sub_i32 s22, s93, 63
	s_cmp_gt_i32 s22, s91
	s_cbranch_scc1 .Lmla_skiprd_o
	v_add_u32_e32 v96, v141, v126
	ds_read_b128 v[192:195], v96 offset:22016
	ds_read_b128 v[196:199], v96 offset:22048
	ds_read_b128 v[200:203], v96 offset:22080
	ds_read_b128 v[204:207], v96 offset:22112
	ds_read_b128 v[208:211], v96 offset:22144
	ds_read_b128 v[212:215], v96 offset:22176
	ds_read_b128 v[216:219], v96 offset:28672
	ds_read_b128 v[162:165], v96 offset:28704
	ds_read_b128 v[166:169], v96 offset:28736
	ds_read_b128 v[170:173], v96 offset:28768
	ds_read_b128 v[174:177], v96 offset:28800
	ds_read_b128 v[178:181], v96 offset:28832
.Lmla_skiprd_o:
	s_cmp_ge_u32 s92, s89
	s_cbranch_scc1 .LBB0_1465
	v_add_co_u32_e32 v32, vcc, 0xffffe000, v130
	s_nop 1
	v_addc_co_u32_e32 v33, vcc, -1, v131, vcc
	global_load_dwordx4 v[72:75], v[32:33], off
	s_and_saveexec_b64 s[72:73], s[8:9]
	s_cbranch_execz .LBB0_1461
	global_load_dwordx4 v[64:67], v[130:131], off

.LBB0_1466:
	v_xor_b32_e32 v32, 0x80000000, v148
	v_mov_b32_e32 v33, v32
	v_mov_b32_e32 v34, v32
	v_mov_b32_e32 v35, v32
	v_mov_b32_e32 v36, v32
	v_mov_b32_e32 v37, v32
	v_mov_b32_e32 v38, v32
	v_mov_b32_e32 v39, v32
	v_mov_b32_e32 v40, v32
	v_mov_b32_e32 v41, v32
	v_mov_b32_e32 v42, v32
	v_mov_b32_e32 v43, v32
	v_mov_b32_e32 v44, v32
	v_mov_b32_e32 v45, v32
	v_mov_b32_e32 v46, v32
	v_mov_b32_e32 v47, v32
	v_add_u32_e32 v182, v143, v144
	v_add_u32_e32 v183, 0x8800, v182
	v_add_u32_e32 v184, 0x9800, v182
	v_xor_b32_e32 v185, 32, v225
	v_lshlrev_b32_e32 v185, 2, v185
	s_cmp_le_i32 s93, s90
	s_waitcnt lgkmcnt(11)
	v_mfma_f32_32x32x16_bf16 v[48:63], v[192:195], v[80:83], v[32:47]
	ds_read2_b64 v[192:195], v183 offset0:64 offset1:66
	s_waitcnt lgkmcnt(11)
	v_mfma_f32_32x32x16_bf16 v[48:63], v[196:199], v[84:87], v[48:63]
	ds_read2_b64 v[196:199], v184 offset0:96 offset1:98
	s_waitcnt lgkmcnt(11)
	v_mfma_f32_32x32x16_bf16 v[48:63], v[200:203], v[88:91], v[48:63]
	ds_read2_b64 v[200:203], v183 offset0:68 offset1:70
	s_waitcnt lgkmcnt(11)
	v_mfma_f32_32x32x16_bf16 v[48:63], v[204:207], v[92:95], v[48:63]
	ds_read2_b64 v[204:207], v184 offset0:100 offset1:102
	s_waitcnt lgkmcnt(11)
	v_mfma_f32_32x32x16_bf16 v[48:63], v[208:211], v[100:103], v[48:63]
	ds_read2_b64 v[208:211], v183 offset0:72 offset1:74
	s_waitcnt lgkmcnt(11)
	v_mfma_f32_32x32x16_bf16 v[48:63], v[212:215], v[104:107], v[48:63]
	ds_read2_b64 v[212:215], v184 offset0:104 offset1:106
	s_waitcnt lgkmcnt(11)
	v_mfma_f32_32x32x16_bf16 v[32:47], v[216:219], v[80:83], v[32:47]
	ds_read2_b64 v[216:219], v183 offset0:76 offset1:78
	s_waitcnt lgkmcnt(11)
	v_mfma_f32_32x32x16_bf16 v[32:47], v[162:165], v[84:87], v[32:47]
	ds_read2_b64 v[162:165], v184 offset0:108 offset1:110
	s_waitcnt lgkmcnt(11)
	v_mfma_f32_32x32x16_bf16 v[32:47], v[166:169], v[88:91], v[32:47]
	s_waitcnt lgkmcnt(10)
	v_mfma_f32_32x32x16_bf16 v[32:47], v[170:173], v[92:95], v[32:47]
	s_waitcnt lgkmcnt(9)
	v_mfma_f32_32x32x16_bf16 v[32:47], v[174:177], v[100:103], v[32:47]
	s_waitcnt lgkmcnt(8)
	v_mfma_f32_32x32x16_bf16 v[32:47], v[178:181], v[104:107], v[32:47]
	s_cbranch_scc1 .LBB0_1468
	v_add_u32_e32 v96, s93, v140
	v_subrev_u32_e32 v99, 31, v96
	v_subrev_u32_e32 v98, 63, v96
	v_cmp_le_i32_e32 vcc, v99, v142
	s_nop 6
	v_cndmask_b32_e32 v32, v235, v32, vcc
	v_cmp_lt_i32_e32 vcc, v98, v142
	s_nop 1
	v_cndmask_b32_e32 v49, v235, v49, vcc
	v_cmp_le_i32_e32 vcc, v98, v142
	v_subrev_u32_e32 v98, 30, v96
	s_nop 0
	v_cndmask_b32_e32 v48, v235, v48, vcc
	v_cmp_le_i32_e32 vcc, v98, v142
	v_subrev_u32_e32 v98, 61, v96
	s_nop 0
	v_cndmask_b32_e32 v33, v235, v33, vcc
	v_cmp_le_i32_e32 vcc, v98, v142
	v_subrev_u32_e32 v98, 29, v96
	s_nop 0
	v_cndmask_b32_e32 v50, v235, v50, vcc
	v_cmp_le_i32_e32 vcc, v98, v142
	v_subrev_u32_e32 v98, 60, v96
	s_nop 0
	v_cndmask_b32_e32 v34, v235, v34, vcc
	v_cmp_le_i32_e32 vcc, v98, v142
	v_subrev_u32_e32 v98, 28, v96
	s_nop 0
	v_cndmask_b32_e32 v51, v235, v51, vcc
	v_cmp_le_i32_e32 vcc, v98, v142
	v_subrev_u32_e32 v98, 55, v96
	s_nop 0
	v_cndmask_b32_e32 v35, v235, v35, vcc
	v_cmp_le_i32_e32 vcc, v98, v142
	v_subrev_u32_e32 v98, 23, v96
	s_nop 0
	v_cndmask_b32_e32 v52, v235, v52, vcc
	v_cmp_le_i32_e32 vcc, v98, v142
	v_subrev_u32_e32 v98, 54, v96
	s_nop 0
	v_cndmask_b32_e32 v36, v235, v36, vcc
	v_cmp_le_i32_e32 vcc, v98, v142
	v_subrev_u32_e32 v98, 22, v96
	s_nop 0
	v_cndmask_b32_e32 v53, v235, v53, vcc
	v_cmp_le_i32_e32 vcc, v98, v142
	v_subrev_u32_e32 v98, 53, v96
	s_nop 0
	v_cndmask_b32_e32 v37, v235, v37, vcc
	v_cmp_le_i32_e32 vcc, v98, v142
	v_subrev_u32_e32 v98, 21, v96
	s_nop 0
	v_cndmask_b32_e32 v54, v235, v54, vcc
	v_cmp_le_i32_e32 vcc, v98, v142
	v_subrev_u32_e32 v98, 52, v96
	s_nop 0
	v_cndmask_b32_e32 v38, v235, v38, vcc
	v_cmp_le_i32_e32 vcc, v98, v142
	v_subrev_u32_e32 v98, 20, v96
	s_nop 0
	v_cndmask_b32_e32 v55, v235, v55, vcc
	v_cmp_le_i32_e32 vcc, v98, v142
	v_subrev_u32_e32 v98, 47, v96
	s_nop 0
	v_cndmask_b32_e32 v39, v235, v39, vcc
	v_cmp_le_i32_e32 vcc, v98, v142
	v_add_u32_e32 v98, -15, v96
	s_nop 0
	v_cndmask_b32_e32 v56, v235, v56, vcc
	v_cmp_le_i32_e32 vcc, v98, v142
	v_subrev_u32_e32 v98, 46, v96
	s_nop 0
	v_cndmask_b32_e32 v40, v235, v40, vcc
	v_cmp_le_i32_e32 vcc, v98, v142
	v_add_u32_e32 v98, -14, v96
	s_nop 0
	v_cndmask_b32_e32 v57, v235, v57, vcc
	v_cmp_le_i32_e32 vcc, v98, v142
	v_subrev_u32_e32 v98, 45, v96
	s_nop 0
	v_cndmask_b32_e32 v41, v235, v41, vcc
	v_cmp_le_i32_e32 vcc, v98, v142
	v_add_u32_e32 v98, -13, v96
	s_nop 0
	v_cndmask_b32_e32 v58, v235, v58, vcc
	v_cmp_le_i32_e32 vcc, v98, v142
	v_subrev_u32_e32 v98, 44, v96
	s_nop 0
	v_cndmask_b32_e32 v42, v235, v42, vcc
	v_cmp_le_i32_e32 vcc, v98, v142
	v_add_u32_e32 v98, -12, v96
	s_nop 0
	v_cndmask_b32_e32 v59, v235, v59, vcc
	v_cmp_le_i32_e32 vcc, v98, v142
	v_subrev_u32_e32 v98, 39, v96
	s_nop 0
	v_cndmask_b32_e32 v43, v235, v43, vcc
	v_cmp_le_i32_e32 vcc, v98, v142
	v_add_u32_e32 v98, -7, v96
	s_nop 0
	v_cndmask_b32_e32 v60, v235, v60, vcc
	v_cmp_le_i32_e32 vcc, v98, v142
	v_subrev_u32_e32 v98, 38, v96
	s_nop 0
	v_cndmask_b32_e32 v44, v235, v44, vcc
	v_cmp_le_i32_e32 vcc, v98, v142
	v_add_u32_e32 v98, -6, v96
	s_nop 0
	v_cndmask_b32_e32 v61, v235, v61, vcc
	v_cmp_le_i32_e32 vcc, v98, v142
	v_subrev_u32_e32 v98, 37, v96
	s_nop 0
	v_cndmask_b32_e32 v45, v235, v45, vcc
	v_cmp_le_i32_e32 vcc, v98, v142
	v_add_u32_e32 v98, -5, v96
	s_nop 0
	v_cndmask_b32_e32 v62, v235, v62, vcc
	v_cmp_le_i32_e32 vcc, v98, v142
	v_subrev_u32_e32 v98, 36, v96
	v_add_u32_e32 v96, -4, v96
	v_cndmask_b32_e32 v46, v235, v46, vcc
	v_cmp_le_i32_e32 vcc, v98, v142
	s_nop 1
	v_cndmask_b32_e32 v63, v235, v63, vcc
	v_cmp_le_i32_e32 vcc, v96, v142
	s_nop 1
	v_cndmask_b32_e32 v47, v235, v47, vcc
